# W_fo prep item (w_fourier @ w_out rows 768..1023) moved from a serialised f32 VALU loop to v_mfma_f32_16x16x4_f32 (f32 operands, f32 accumulate)
# speedup vs baseline: 1.0972x; 1.0034x over previous
.LBB0_22:
	s_cmp_lt_i32 s29, 0
	s_cbranch_scc1 .LBB0_14
	s_cmpk_gt_u32 s29, 0xbf
	s_mov_b64 s[40:41], -1
	s_barrier
	s_cbranch_scc0 .LBB0_67
	s_cmpk_gt_u32 s29, 0x13f
	s_cbranch_scc0 .LBB0_49
	v_writelane_b32 v163, s0, 0
	v_writelane_b32 v163, s1, 1
	v_writelane_b32 v163, s2, 2
	v_writelane_b32 v163, s3, 3
	v_writelane_b32 v163, s4, 4
	v_writelane_b32 v163, s5, 5
	v_writelane_b32 v163, s6, 6
	v_writelane_b32 v163, s7, 7
	v_writelane_b32 v163, s8, 8
	v_writelane_b32 v163, s9, 9
	v_writelane_b32 v163, s10, 10
	v_writelane_b32 v163, s11, 11
	v_writelane_b32 v163, s12, 12
	v_writelane_b32 v163, s13, 13
	v_writelane_b32 v163, s14, 14
	v_writelane_b32 v163, s15, 15
	s_add_i32 s0, s29, 0xfffffec0
	s_lshr_b32 s1, s0, 6
	s_and_b32 s2, s0, 63
	s_lshl_b32 s2, s2, 4
	v_readlane_b32 s4, v251, 63
	v_readlane_b32 s5, v252, 0
	v_readlane_b32 s6, v251, 4
	v_readlane_b32 s7, v251, 5
	v_readlane_b32 s8, v251, 18
	v_readlane_b32 s9, v251, 19
	v_mbcnt_lo_u32_b32 v160, -1, 0
	v_mbcnt_hi_u32_b32 v160, -1, v160
	v_and_b32_e32 v214, 15, v160
	v_lshrrev_b32_e32 v215, 4, v160
	v_readfirstlane_b32 s10, v76
	s_lshr_b32 s10, s10, 6
	s_lshl_b32 s11, s1, 18
	s_add_u32 s4, s4, s11
	s_addc_u32 s5, s5, 0
	s_lshl_b32 s11, s1, 22
	s_add_u32 s6, s6, s11
	s_addc_u32 s7, s7, 0
	s_add_u32 s6, s6, 0x300000
	s_addc_u32 s7, s7, 0
	s_mul_i32 s11, s1, 0x1800000
	s_add_u32 s8, s8, s11
	s_addc_u32 s9, s9, 0
	s_add_u32 s8, s8, 0x680000
	s_addc_u32 s9, s9, 0
	s_lshl_b32 s11, s10, 5
	v_add_u32_e32 v248, s11, v214
	v_lshlrev_b32_e32 v248, 10, v248
	v_lshl_add_u32 v248, v215, 4, v248
	v_add_u32_e32 v249, 0x4000, v248
	v_add_u32_e32 v162, s2, v214
	v_lshlrev_b32_e32 v162, 2, v162
	v_lshl_add_u32 v162, v215, 14, v162
	v_add_u32_e32 v162, 0x1000, v162
	v_add_u32_e32 v210, 0x2000, v162
	v_mov_b32_e32 v152, 0
	v_mov_b32_e32 v156, 0
	v_mov_b32_e32 v153, 0
	v_mov_b32_e32 v157, 0
	v_mov_b32_e32 v154, 0
	v_mov_b32_e32 v158, 0
	v_mov_b32_e32 v155, 0
	v_mov_b32_e32 v159, 0
	s_add_u32 s12, s6, 0x0
	s_addc_u32 s13, s7, 0
	global_load_dwordx4 v[164:167], v248, s[4:5] offset:0
	global_load_dwordx4 v[168:171], v249, s[4:5] offset:0
	global_load_dword v172, v162, s[12:13] offset:-4096
	global_load_dword v173, v162, s[12:13]
	global_load_dword v174, v210, s[12:13] offset:-4096
	global_load_dword v175, v210, s[12:13]
	s_add_u32 s12, s6, 0x10000
	s_addc_u32 s13, s7, 0
	global_load_dwordx4 v[176:179], v248, s[4:5] offset:64
	global_load_dwordx4 v[180:183], v249, s[4:5] offset:64
	global_load_dword v184, v162, s[12:13] offset:-4096
	global_load_dword v185, v162, s[12:13]
	global_load_dword v186, v210, s[12:13] offset:-4096
	global_load_dword v187, v210, s[12:13]
	s_add_u32 s12, s6, 0x20000
	s_addc_u32 s13, s7, 0
	global_load_dwordx4 v[188:191], v248, s[4:5] offset:128
	global_load_dwordx4 v[192:195], v249, s[4:5] offset:128
	global_load_dword v196, v162, s[12:13] offset:-4096
	global_load_dword v197, v162, s[12:13]
	global_load_dword v198, v210, s[12:13] offset:-4096
	global_load_dword v199, v210, s[12:13]
	s_add_u32 s12, s6, 0x30000
	s_addc_u32 s13, s7, 0
	global_load_dwordx4 v[200:203], v248, s[4:5] offset:192
	global_load_dwordx4 v[204:207], v249, s[4:5] offset:192
	global_load_dword v220, v162, s[12:13] offset:-4096
	global_load_dword v221, v162, s[12:13]
	global_load_dword v222, v210, s[12:13] offset:-4096
	global_load_dword v223, v210, s[12:13]
	s_add_u32 s12, s6, 0x40000
	s_addc_u32 s13, s7, 0
	global_load_dwordx4 v[224:227], v248, s[4:5] offset:256
	global_load_dwordx4 v[228:231], v249, s[4:5] offset:256
	global_load_dword v232, v162, s[12:13] offset:-4096
	global_load_dword v233, v162, s[12:13]
	global_load_dword v234, v210, s[12:13] offset:-4096
	global_load_dword v235, v210, s[12:13]
	s_waitcnt vmcnt(24)
	v_mfma_f32_16x16x4_f32 v[152:155], v164, v172, v[152:155]
	v_mfma_f32_16x16x4_f32 v[156:159], v168, v172, v[156:159]
	v_mfma_f32_16x16x4_f32 v[152:155], v165, v173, v[152:155]
	v_mfma_f32_16x16x4_f32 v[156:159], v169, v173, v[156:159]
	v_mfma_f32_16x16x4_f32 v[152:155], v166, v174, v[152:155]
	v_mfma_f32_16x16x4_f32 v[156:159], v170, v174, v[156:159]
	v_mfma_f32_16x16x4_f32 v[152:155], v167, v175, v[152:155]
	v_mfma_f32_16x16x4_f32 v[156:159], v171, v175, v[156:159]
	s_add_u32 s12, s6, 0x50000
	s_addc_u32 s13, s7, 0
	global_load_dwordx4 v[164:167], v248, s[4:5] offset:320
	global_load_dwordx4 v[168:171], v249, s[4:5] offset:320
	global_load_dword v172, v162, s[12:13] offset:-4096
	global_load_dword v173, v162, s[12:13]
	global_load_dword v174, v210, s[12:13] offset:-4096
	global_load_dword v175, v210, s[12:13]
	s_waitcnt vmcnt(24)
	v_mfma_f32_16x16x4_f32 v[152:155], v176, v184, v[152:155]
	v_mfma_f32_16x16x4_f32 v[156:159], v180, v184, v[156:159]
	v_mfma_f32_16x16x4_f32 v[152:155], v177, v185, v[152:155]
	v_mfma_f32_16x16x4_f32 v[156:159], v181, v185, v[156:159]
	v_mfma_f32_16x16x4_f32 v[152:155], v178, v186, v[152:155]
	v_mfma_f32_16x16x4_f32 v[156:159], v182, v186, v[156:159]
	v_mfma_f32_16x16x4_f32 v[152:155], v179, v187, v[152:155]
	v_mfma_f32_16x16x4_f32 v[156:159], v183, v187, v[156:159]
	s_add_u32 s12, s6, 0x60000
	s_addc_u32 s13, s7, 0
	global_load_dwordx4 v[176:179], v248, s[4:5] offset:384
	global_load_dwordx4 v[180:183], v249, s[4:5] offset:384
	global_load_dword v184, v162, s[12:13] offset:-4096
	global_load_dword v185, v162, s[12:13]
	global_load_dword v186, v210, s[12:13] offset:-4096
	global_load_dword v187, v210, s[12:13]
	s_waitcnt vmcnt(24)
	v_mfma_f32_16x16x4_f32 v[152:155], v188, v196, v[152:155]
	v_mfma_f32_16x16x4_f32 v[156:159], v192, v196, v[156:159]
	v_mfma_f32_16x16x4_f32 v[152:155], v189, v197, v[152:155]
	v_mfma_f32_16x16x4_f32 v[156:159], v193, v197, v[156:159]
	v_mfma_f32_16x16x4_f32 v[152:155], v190, v198, v[152:155]
	v_mfma_f32_16x16x4_f32 v[156:159], v194, v198, v[156:159]
	v_mfma_f32_16x16x4_f32 v[152:155], v191, v199, v[152:155]
	v_mfma_f32_16x16x4_f32 v[156:159], v195, v199, v[156:159]
	s_add_u32 s12, s6, 0x70000
	s_addc_u32 s13, s7, 0
	global_load_dwordx4 v[188:191], v248, s[4:5] offset:448
	global_load_dwordx4 v[192:195], v249, s[4:5] offset:448
	global_load_dword v196, v162, s[12:13] offset:-4096
	global_load_dword v197, v162, s[12:13]
	global_load_dword v198, v210, s[12:13] offset:-4096
	global_load_dword v199, v210, s[12:13]
	s_waitcnt vmcnt(24)
	v_mfma_f32_16x16x4_f32 v[152:155], v200, v220, v[152:155]
	v_mfma_f32_16x16x4_f32 v[156:159], v204, v220, v[156:159]
	v_mfma_f32_16x16x4_f32 v[152:155], v201, v221, v[152:155]
	v_mfma_f32_16x16x4_f32 v[156:159], v205, v221, v[156:159]
	v_mfma_f32_16x16x4_f32 v[152:155], v202, v222, v[152:155]
	v_mfma_f32_16x16x4_f32 v[156:159], v206, v222, v[156:159]
	v_mfma_f32_16x16x4_f32 v[152:155], v203, v223, v[152:155]
	v_mfma_f32_16x16x4_f32 v[156:159], v207, v223, v[156:159]
	s_add_u32 s12, s6, 0x80000
	s_addc_u32 s13, s7, 0
	global_load_dwordx4 v[200:203], v248, s[4:5] offset:512
	global_load_dwordx4 v[204:207], v249, s[4:5] offset:512
	global_load_dword v220, v162, s[12:13] offset:-4096
	global_load_dword v221, v162, s[12:13]
	global_load_dword v222, v210, s[12:13] offset:-4096
	global_load_dword v223, v210, s[12:13]
	s_waitcnt vmcnt(24)
	v_mfma_f32_16x16x4_f32 v[152:155], v224, v232, v[152:155]
	v_mfma_f32_16x16x4_f32 v[156:159], v228, v232, v[156:159]
	v_mfma_f32_16x16x4_f32 v[152:155], v225, v233, v[152:155]
	v_mfma_f32_16x16x4_f32 v[156:159], v229, v233, v[156:159]
	v_mfma_f32_16x16x4_f32 v[152:155], v226, v234, v[152:155]
	v_mfma_f32_16x16x4_f32 v[156:159], v230, v234, v[156:159]
	v_mfma_f32_16x16x4_f32 v[152:155], v227, v235, v[152:155]
	v_mfma_f32_16x16x4_f32 v[156:159], v231, v235, v[156:159]
	s_add_u32 s12, s6, 0x90000
	s_addc_u32 s13, s7, 0
	global_load_dwordx4 v[224:227], v248, s[4:5] offset:576
	global_load_dwordx4 v[228:231], v249, s[4:5] offset:576
	global_load_dword v232, v162, s[12:13] offset:-4096
	global_load_dword v233, v162, s[12:13]
	global_load_dword v234, v210, s[12:13] offset:-4096
	global_load_dword v235, v210, s[12:13]
	s_waitcnt vmcnt(24)
	v_mfma_f32_16x16x4_f32 v[152:155], v164, v172, v[152:155]
	v_mfma_f32_16x16x4_f32 v[156:159], v168, v172, v[156:159]
	v_mfma_f32_16x16x4_f32 v[152:155], v165, v173, v[152:155]
	v_mfma_f32_16x16x4_f32 v[156:159], v169, v173, v[156:159]
	v_mfma_f32_16x16x4_f32 v[152:155], v166, v174, v[152:155]
	v_mfma_f32_16x16x4_f32 v[156:159], v170, v174, v[156:159]
	v_mfma_f32_16x16x4_f32 v[152:155], v167, v175, v[152:155]
	v_mfma_f32_16x16x4_f32 v[156:159], v171, v175, v[156:159]
	s_add_u32 s12, s6, 0xa0000
	s_addc_u32 s13, s7, 0
	global_load_dwordx4 v[164:167], v248, s[4:5] offset:640
	global_load_dwordx4 v[168:171], v249, s[4:5] offset:640
	global_load_dword v172, v162, s[12:13] offset:-4096
	global_load_dword v173, v162, s[12:13]
	global_load_dword v174, v210, s[12:13] offset:-4096
	global_load_dword v175, v210, s[12:13]
	s_waitcnt vmcnt(24)
	v_mfma_f32_16x16x4_f32 v[152:155], v176, v184, v[152:155]
	v_mfma_f32_16x16x4_f32 v[156:159], v180, v184, v[156:159]
	v_mfma_f32_16x16x4_f32 v[152:155], v177, v185, v[152:155]
	v_mfma_f32_16x16x4_f32 v[156:159], v181, v185, v[156:159]
	v_mfma_f32_16x16x4_f32 v[152:155], v178, v186, v[152:155]
	v_mfma_f32_16x16x4_f32 v[156:159], v182, v186, v[156:159]
	v_mfma_f32_16x16x4_f32 v[152:155], v179, v187, v[152:155]
	v_mfma_f32_16x16x4_f32 v[156:159], v183, v187, v[156:159]
	s_add_u32 s12, s6, 0xb0000
	s_addc_u32 s13, s7, 0
	global_load_dwordx4 v[176:179], v248, s[4:5] offset:704
	global_load_dwordx4 v[180:183], v249, s[4:5] offset:704
	global_load_dword v184, v162, s[12:13] offset:-4096
	global_load_dword v185, v162, s[12:13]
	global_load_dword v186, v210, s[12:13] offset:-4096
	global_load_dword v187, v210, s[12:13]
	s_waitcnt vmcnt(24)
	v_mfma_f32_16x16x4_f32 v[152:155], v188, v196, v[152:155]
	v_mfma_f32_16x16x4_f32 v[156:159], v192, v196, v[156:159]
	v_mfma_f32_16x16x4_f32 v[152:155], v189, v197, v[152:155]
	v_mfma_f32_16x16x4_f32 v[156:159], v193, v197, v[156:159]
	v_mfma_f32_16x16x4_f32 v[152:155], v190, v198, v[152:155]
	v_mfma_f32_16x16x4_f32 v[156:159], v194, v198, v[156:159]
	v_mfma_f32_16x16x4_f32 v[152:155], v191, v199, v[152:155]
	v_mfma_f32_16x16x4_f32 v[156:159], v195, v199, v[156:159]
	s_add_u32 s12, s6, 0xc0000
	s_addc_u32 s13, s7, 0
	global_load_dwordx4 v[188:191], v248, s[4:5] offset:768
	global_load_dwordx4 v[192:195], v249, s[4:5] offset:768
	global_load_dword v196, v162, s[12:13] offset:-4096
	global_load_dword v197, v162, s[12:13]
	global_load_dword v198, v210, s[12:13] offset:-4096
	global_load_dword v199, v210, s[12:13]
	s_waitcnt vmcnt(24)
	v_mfma_f32_16x16x4_f32 v[152:155], v200, v220, v[152:155]
	v_mfma_f32_16x16x4_f32 v[156:159], v204, v220, v[156:159]
	v_mfma_f32_16x16x4_f32 v[152:155], v201, v221, v[152:155]
	v_mfma_f32_16x16x4_f32 v[156:159], v205, v221, v[156:159]
	v_mfma_f32_16x16x4_f32 v[152:155], v202, v222, v[152:155]
	v_mfma_f32_16x16x4_f32 v[156:159], v206, v222, v[156:159]
	v_mfma_f32_16x16x4_f32 v[152:155], v203, v223, v[152:155]
	v_mfma_f32_16x16x4_f32 v[156:159], v207, v223, v[156:159]
	s_add_u32 s12, s6, 0xd0000
	s_addc_u32 s13, s7, 0
	global_load_dwordx4 v[200:203], v248, s[4:5] offset:832
	global_load_dwordx4 v[204:207], v249, s[4:5] offset:832
	global_load_dword v220, v162, s[12:13] offset:-4096
	global_load_dword v221, v162, s[12:13]
	global_load_dword v222, v210, s[12:13] offset:-4096
	global_load_dword v223, v210, s[12:13]
	s_waitcnt vmcnt(24)
	v_mfma_f32_16x16x4_f32 v[152:155], v224, v232, v[152:155]
	v_mfma_f32_16x16x4_f32 v[156:159], v228, v232, v[156:159]
	v_mfma_f32_16x16x4_f32 v[152:155], v225, v233, v[152:155]
	v_mfma_f32_16x16x4_f32 v[156:159], v229, v233, v[156:159]
	v_mfma_f32_16x16x4_f32 v[152:155], v226, v234, v[152:155]
	v_mfma_f32_16x16x4_f32 v[156:159], v230, v234, v[156:159]
	v_mfma_f32_16x16x4_f32 v[152:155], v227, v235, v[152:155]
	v_mfma_f32_16x16x4_f32 v[156:159], v231, v235, v[156:159]
	s_add_u32 s12, s6, 0xe0000
	s_addc_u32 s13, s7, 0
	global_load_dwordx4 v[224:227], v248, s[4:5] offset:896
	global_load_dwordx4 v[228:231], v249, s[4:5] offset:896
	global_load_dword v232, v162, s[12:13] offset:-4096
	global_load_dword v233, v162, s[12:13]
	global_load_dword v234, v210, s[12:13] offset:-4096
	global_load_dword v235, v210, s[12:13]
	s_waitcnt vmcnt(24)
	v_mfma_f32_16x16x4_f32 v[152:155], v164, v172, v[152:155]
	v_mfma_f32_16x16x4_f32 v[156:159], v168, v172, v[156:159]
	v_mfma_f32_16x16x4_f32 v[152:155], v165, v173, v[152:155]
	v_mfma_f32_16x16x4_f32 v[156:159], v169, v173, v[156:159]
	v_mfma_f32_16x16x4_f32 v[152:155], v166, v174, v[152:155]
	v_mfma_f32_16x16x4_f32 v[156:159], v170, v174, v[156:159]
	v_mfma_f32_16x16x4_f32 v[152:155], v167, v175, v[152:155]
	v_mfma_f32_16x16x4_f32 v[156:159], v171, v175, v[156:159]
	s_add_u32 s12, s6, 0xf0000
	s_addc_u32 s13, s7, 0
	global_load_dwordx4 v[164:167], v248, s[4:5] offset:960
	global_load_dwordx4 v[168:171], v249, s[4:5] offset:960
	global_load_dword v172, v162, s[12:13] offset:-4096
	global_load_dword v173, v162, s[12:13]
	global_load_dword v174, v210, s[12:13] offset:-4096
	global_load_dword v175, v210, s[12:13]
	s_waitcnt vmcnt(24)
	v_mfma_f32_16x16x4_f32 v[152:155], v176, v184, v[152:155]
	v_mfma_f32_16x16x4_f32 v[156:159], v180, v184, v[156:159]
	v_mfma_f32_16x16x4_f32 v[152:155], v177, v185, v[152:155]
	v_mfma_f32_16x16x4_f32 v[156:159], v181, v185, v[156:159]
	v_mfma_f32_16x16x4_f32 v[152:155], v178, v186, v[152:155]
	v_mfma_f32_16x16x4_f32 v[156:159], v182, v186, v[156:159]
	v_mfma_f32_16x16x4_f32 v[152:155], v179, v187, v[152:155]
	v_mfma_f32_16x16x4_f32 v[156:159], v183, v187, v[156:159]
	s_waitcnt vmcnt(18)
	v_mfma_f32_16x16x4_f32 v[152:155], v188, v196, v[152:155]
	v_mfma_f32_16x16x4_f32 v[156:159], v192, v196, v[156:159]
	v_mfma_f32_16x16x4_f32 v[152:155], v189, v197, v[152:155]
	v_mfma_f32_16x16x4_f32 v[156:159], v193, v197, v[156:159]
	v_mfma_f32_16x16x4_f32 v[152:155], v190, v198, v[152:155]
	v_mfma_f32_16x16x4_f32 v[156:159], v194, v198, v[156:159]
	v_mfma_f32_16x16x4_f32 v[152:155], v191, v199, v[152:155]
	v_mfma_f32_16x16x4_f32 v[156:159], v195, v199, v[156:159]
	s_waitcnt vmcnt(12)
	v_mfma_f32_16x16x4_f32 v[152:155], v200, v220, v[152:155]
	v_mfma_f32_16x16x4_f32 v[156:159], v204, v220, v[156:159]
	v_mfma_f32_16x16x4_f32 v[152:155], v201, v221, v[152:155]
	v_mfma_f32_16x16x4_f32 v[156:159], v205, v221, v[156:159]
	v_mfma_f32_16x16x4_f32 v[152:155], v202, v222, v[152:155]
	v_mfma_f32_16x16x4_f32 v[156:159], v206, v222, v[156:159]
	v_mfma_f32_16x16x4_f32 v[152:155], v203, v223, v[152:155]
	v_mfma_f32_16x16x4_f32 v[156:159], v207, v223, v[156:159]
	s_waitcnt vmcnt(6)
	v_mfma_f32_16x16x4_f32 v[152:155], v224, v232, v[152:155]
	v_mfma_f32_16x16x4_f32 v[156:159], v228, v232, v[156:159]
	v_mfma_f32_16x16x4_f32 v[152:155], v225, v233, v[152:155]
	v_mfma_f32_16x16x4_f32 v[156:159], v229, v233, v[156:159]
	v_mfma_f32_16x16x4_f32 v[152:155], v226, v234, v[152:155]
	v_mfma_f32_16x16x4_f32 v[156:159], v230, v234, v[156:159]
	v_mfma_f32_16x16x4_f32 v[152:155], v227, v235, v[152:155]
	v_mfma_f32_16x16x4_f32 v[156:159], v231, v235, v[156:159]
	s_waitcnt vmcnt(0)
	v_mfma_f32_16x16x4_f32 v[152:155], v164, v172, v[152:155]
	v_mfma_f32_16x16x4_f32 v[156:159], v168, v172, v[156:159]
	v_mfma_f32_16x16x4_f32 v[152:155], v165, v173, v[152:155]
	v_mfma_f32_16x16x4_f32 v[156:159], v169, v173, v[156:159]
	v_mfma_f32_16x16x4_f32 v[152:155], v166, v174, v[152:155]
	v_mfma_f32_16x16x4_f32 v[156:159], v170, v174, v[156:159]
	v_mfma_f32_16x16x4_f32 v[152:155], v167, v175, v[152:155]
	v_mfma_f32_16x16x4_f32 v[156:159], v171, v175, v[156:159]
	s_nop 7
	s_nop 7
	v_add_u32_e32 v211, s2, v214
	v_lshlrev_b32_e32 v211, 10, v211
	v_lshl_add_u32 v211, v215, 2, v211
	s_add_i32 s11, s11, 0x300
	v_add_u32_e32 v211, s11, v211
	v_lshlrev_b32_e32 v211, 1, v211
	v_cvt_pk_bf16_f32 v152, v152, v153
	v_cvt_pk_bf16_f32 v153, v154, v155
	v_cvt_pk_bf16_f32 v156, v156, v157
	v_cvt_pk_bf16_f32 v157, v158, v159
	global_store_dwordx2 v211, v[152:153], s[8:9]
	global_store_dwordx2 v211, v[156:157], s[8:9] offset:32
	v_readlane_b32 s0, v163, 0
	v_readlane_b32 s1, v163, 1
	v_readlane_b32 s2, v163, 2
	v_readlane_b32 s3, v163, 3
	v_readlane_b32 s4, v163, 4
	v_readlane_b32 s5, v163, 5
	v_readlane_b32 s6, v163, 6
	v_readlane_b32 s7, v163, 7
	v_readlane_b32 s8, v163, 8
	v_readlane_b32 s9, v163, 9
	v_readlane_b32 s10, v163, 10
	v_readlane_b32 s11, v163, 11
	v_readlane_b32 s12, v163, 12
	v_readlane_b32 s13, v163, 13
	v_readlane_b32 s14, v163, 14
	v_readlane_b32 s15, v163, 15
	s_nop 3
	s_mov_b64 s[40:41], 0
